# g3 epilogue: the 8 per-head output-gain loads hoisted ahead of the first store (one round trip, no per-store vmcnt(0)); on top of thin<0,22> LDS re-layout
# baseline (speedup 1.0000x reference)
.LBB0_616:
	s_or_b64 exec, exec, s[12:13]
	v_pk_mul_f32 v[80:81], v[28:29], v[28:29]
	v_pk_mul_f32 v[82:83], v[24:25], v[24:25]
	v_pk_mul_f32 v[32:33], v[30:31], v[30:31]
	v_pk_mul_f32 v[34:35], v[26:27], v[26:27]
	v_mov_b32_e32 v84, v80
	v_mov_b32_e32 v85, v82
	v_mov_b32_e32 v82, v81
	v_pk_add_f32 v[80:81], v[84:85], v[82:83]
	v_mov_b32_e32 v82, v32
	v_mov_b32_e32 v83, v34
	v_readlane_b32 s12, v249, 54
	v_pk_add_f32 v[80:81], v[82:83], v[80:81]
	v_mov_b32_e32 v34, v33
	v_lshlrev_b32_e32 v65, 2, v64
	v_readlane_b32 s13, v249, 55
	v_pk_add_f32 v[80:81], v[34:35], v[80:81]
	v_pk_mul_f32 v[76:77], v[16:17], v[16:17]
	v_pk_mul_f32 v[78:79], v[20:21], v[20:21]
	v_pk_mul_f32 v[72:73], v[18:19], v[18:19]
	v_pk_mul_f32 v[74:75], v[22:23], v[22:23]
	global_load_dwordx4 v[200:203], v65, s[12:13]
	global_load_dwordx4 v[204:207], v65, s[12:13] offset:64
	global_load_dwordx4 v[208:211], v65, s[12:13] offset:128
	global_load_dwordx4 v[212:215], v65, s[12:13] offset:192
	global_load_dwordx4 v[216:219], v65, s[12:13] offset:256
	global_load_dwordx4 v[220:223], v65, s[12:13] offset:320
	global_load_dwordx4 v[224:227], v65, s[12:13] offset:384
	global_load_dwordx4 v[228:231], v65, s[12:13] offset:448
	v_mov_b32_e32 v82, v76
	v_mov_b32_e32 v83, v78
	v_mov_b32_e32 v78, v77
	v_pk_add_f32 v[76:77], v[82:83], v[78:79]
	v_mov_b32_e32 v78, v72
	v_mov_b32_e32 v79, v74
	v_pk_mul_f32 v[68:69], v[8:9], v[8:9]
	v_pk_mul_f32 v[70:71], v[12:13], v[12:13]
	v_pk_add_f32 v[76:77], v[78:79], v[76:77]
	v_mov_b32_e32 v74, v73
	v_pk_mul_f32 v[62:63], v[10:11], v[10:11]
	v_pk_mul_f32 v[66:67], v[14:15], v[14:15]
	v_pk_add_f32 v[72:73], v[74:75], v[76:77]
	v_mov_b32_e32 v74, v68
	v_mov_b32_e32 v75, v70
	v_mov_b32_e32 v70, v69
	v_pk_add_f32 v[68:69], v[74:75], v[70:71]
	v_mov_b32_e32 v70, v62
	v_mov_b32_e32 v71, v66
	v_pk_mul_f32 v[40:41], v[4:5], v[4:5]
	v_pk_mul_f32 v[42:43], v[0:1], v[0:1]
	v_pk_add_f32 v[68:69], v[70:71], v[68:69]
	v_mov_b32_e32 v66, v63
	v_pk_mul_f32 v[36:37], v[6:7], v[6:7]
	v_pk_mul_f32 v[38:39], v[2:3], v[2:3]
	v_pk_add_f32 v[62:63], v[66:67], v[68:69]
	v_mov_b32_e32 v66, v40
	v_mov_b32_e32 v67, v42
	v_mov_b32_e32 v42, v41
	v_pk_add_f32 v[40:41], v[66:67], v[42:43]
	v_mov_b32_e32 v42, v36
	v_mov_b32_e32 v43, v38
	v_pk_add_f32 v[40:41], v[42:43], v[40:41]
	v_mov_b32_e32 v38, v37
	v_pk_add_f32 v[36:37], v[38:39], v[40:41]
	v_add_f32_e32 v38, v80, v81
	v_add_f32_e32 v38, v73, v38
	v_add_f32_e32 v38, v72, v38
	v_add_f32_e32 v38, v63, v38
	v_add_f32_e32 v38, v62, v38
	v_add_f32_e32 v37, v37, v38
	v_and_b32_e32 v38, 64, v183
	v_add_f32_e32 v36, v36, v37
	v_xor_b32_e32 v37, 16, v183
	v_add_u32_e32 v38, 64, v38
	v_cmp_lt_i32_e32 vcc, v37, v38
	v_readlane_b32 s0, v252, 35
	v_ashrrev_i32_e32 v61, 31, v60
	v_cndmask_b32_e32 v37, v183, v37, vcc
	v_lshlrev_b32_e32 v37, 2, v37
	ds_bpermute_b32 v37, v37, v36
	v_readlane_b32 s1, v252, 36
	v_lshlrev_b32_e32 v138, 1, v64
	v_lshlrev_b32_e32 v41, 16, v59
	v_and_b32_e32 v42, 0xffff0000, v59
	s_waitcnt lgkmcnt(0)
	v_add_f32_e32 v36, v36, v37
	v_xor_b32_e32 v37, 32, v183
	v_cmp_lt_i32_e32 vcc, v37, v38
	v_mov_b64_e32 v[38:39], s[6:7]
	s_nop 0
	v_cndmask_b32_e32 v37, v183, v37, vcc
	v_lshlrev_b32_e32 v37, 2, v37
	ds_bpermute_b32 v37, v37, v36
	s_waitcnt lgkmcnt(0)
	v_add_f32_e32 v36, v36, v37
	v_fmamk_f32 v36, v36, 0x3c000000, v177
	v_mul_f32_e32 v37, 0x4b800000, v36
	v_cmp_gt_f32_e32 vcc, s28, v36
	s_nop 1
	v_cndmask_b32_e32 v36, v36, v37, vcc
	v_rsq_f32_e32 v36, v36
	s_nop 0
	v_mul_f32_e32 v37, 0x45800000, v36
	v_cndmask_b32_e32 v40, v36, v37, vcc
	v_lshl_add_u64 v[36:37], v[60:61], 0, s[0:1]
	v_mad_u64_u32 v[38:39], s[0:1], v36, s22, v[38:39]
	v_mad_i32_i24 v39, v37, s22, v39
	v_mul_f32_e32 v28, v28, v40
	v_mul_f32_e32 v29, v29, v40
	v_lshl_add_u64 v[36:37], v[38:39], 0, s[74:75]
	v_lshlrev_b32_e32 v38, 16, v58
	v_and_b32_e32 v39, 0xffff0000, v58
	s_waitcnt vmcnt(0)
	v_mul_f32_e32 v28, v200, v28
	v_mul_f32_e32 v29, v201, v29
	v_mul_f32_e32 v28, v28, v38
	v_mul_f32_e32 v29, v29, v39
	v_cvt_pk_bf16_f32 v28, v28, v29
	v_mul_f32_e32 v29, v30, v40
	v_mul_f32_e32 v30, v31, v40
	v_mul_f32_e32 v29, v202, v29
	v_mul_f32_e32 v30, v203, v30
	v_lshl_add_u64 v[36:37], v[36:37], 0, v[138:139]
	v_mul_f32_e32 v29, v29, v41
	v_mul_f32_e32 v30, v30, v42
	v_cvt_pk_bf16_f32 v29, v29, v30
	v_add_co_u32_e32 v30, vcc, s97, v36
	v_mul_f32_e32 v24, v24, v40
	s_nop 0
	v_addc_co_u32_e32 v31, vcc, 0, v37, vcc
	global_store_dwordx2 v[30:31], v[28:29], off offset:1024
	v_mul_f32_e32 v25, v25, v40
	v_lshlrev_b32_e32 v34, 16, v56
	v_and_b32_e32 v35, 0xffff0000, v56
	v_mul_f32_e32 v26, v26, v40
	v_mul_f32_e32 v27, v27, v40
	v_lshlrev_b32_e32 v38, 16, v57
	v_and_b32_e32 v39, 0xffff0000, v57
	v_lshl_add_u64 v[32:33], v[36:37], 0, s[70:71]
	v_mul_f32_e32 v20, v20, v40
	v_mul_f32_e32 v21, v21, v40
	v_mul_f32_e32 v22, v22, v40
	v_mul_f32_e32 v23, v23, v40
	v_mul_f32_e32 v16, v16, v40
	v_mul_f32_e32 v17, v17, v40
	v_mul_f32_e32 v18, v18, v40
	v_mul_f32_e32 v19, v19, v40
	v_mul_f32_e32 v12, v12, v40
	v_mul_f32_e32 v13, v13, v40
	v_mul_f32_e32 v14, v14, v40
	v_mul_f32_e32 v15, v15, v40
	v_mul_f32_e32 v8, v8, v40
	v_mul_f32_e32 v9, v9, v40
	v_mul_f32_e32 v10, v10, v40
	v_mul_f32_e32 v11, v11, v40
	v_mul_f32_e32 v0, v0, v40
	v_mul_f32_e32 v1, v1, v40
	v_mul_f32_e32 v2, v2, v40
	v_mul_f32_e32 v3, v3, v40
	v_mul_f32_e32 v4, v4, v40
	v_mul_f32_e32 v5, v5, v40
	v_mul_f32_e32 v6, v6, v40
	v_mul_f32_e32 v7, v7, v40
	v_readlane_b32 s74, v249, 43
	v_mul_f32_e32 v24, v204, v24
	v_mul_f32_e32 v25, v205, v25
	v_mul_f32_e32 v26, v206, v26
	v_mul_f32_e32 v27, v207, v27
	v_mul_f32_e32 v24, v24, v34
	v_mul_f32_e32 v25, v25, v35
	v_mul_f32_e32 v26, v26, v38
	v_mul_f32_e32 v27, v27, v39
	v_cvt_pk_bf16_f32 v24, v24, v25
	v_cvt_pk_bf16_f32 v25, v26, v27
	global_store_dwordx2 v[32:33], v[24:25], off offset:32
	v_lshlrev_b32_e32 v28, 16, v54
	v_and_b32_e32 v29, 0xffff0000, v54
	v_lshlrev_b32_e32 v30, 16, v55
	v_and_b32_e32 v31, 0xffff0000, v55
	v_mul_f32_e32 v20, v208, v20
	v_mul_f32_e32 v21, v209, v21
	v_mul_f32_e32 v22, v210, v22
	v_mul_f32_e32 v23, v211, v23
	v_mul_f32_e32 v20, v20, v28
	v_mul_f32_e32 v21, v21, v29
	v_mul_f32_e32 v22, v22, v30
	v_mul_f32_e32 v23, v23, v31
	v_cvt_pk_bf16_f32 v20, v20, v21
	v_cvt_pk_bf16_f32 v21, v22, v23
	global_store_dwordx2 v[32:33], v[20:21], off offset:64
	v_lshlrev_b32_e32 v24, 16, v52
	v_and_b32_e32 v25, 0xffff0000, v52
	v_lshlrev_b32_e32 v26, 16, v53
	v_and_b32_e32 v27, 0xffff0000, v53
	v_mul_f32_e32 v16, v212, v16
	v_mul_f32_e32 v17, v213, v17
	v_mul_f32_e32 v18, v214, v18
	v_mul_f32_e32 v19, v215, v19
	v_mul_f32_e32 v16, v16, v24
	v_mul_f32_e32 v17, v17, v25
	v_mul_f32_e32 v18, v18, v26
	v_mul_f32_e32 v19, v19, v27
	v_cvt_pk_bf16_f32 v16, v16, v17
	v_cvt_pk_bf16_f32 v17, v18, v19
	global_store_dwordx2 v[32:33], v[16:17], off offset:96
	v_lshlrev_b32_e32 v20, 16, v50
	v_and_b32_e32 v21, 0xffff0000, v50
	v_lshlrev_b32_e32 v22, 16, v51
	v_and_b32_e32 v23, 0xffff0000, v51
	v_mul_f32_e32 v12, v216, v12
	v_mul_f32_e32 v13, v217, v13
	v_mul_f32_e32 v14, v218, v14
	v_mul_f32_e32 v15, v219, v15
	v_mul_f32_e32 v12, v12, v20
	v_mul_f32_e32 v13, v13, v21
	v_mul_f32_e32 v14, v14, v22
	v_mul_f32_e32 v15, v15, v23
	v_cvt_pk_bf16_f32 v12, v12, v13
	v_cvt_pk_bf16_f32 v13, v14, v15
	global_store_dwordx2 v[32:33], v[12:13], off offset:128
	v_lshlrev_b32_e32 v16, 16, v48
	v_and_b32_e32 v17, 0xffff0000, v48
	v_lshlrev_b32_e32 v18, 16, v49
	v_and_b32_e32 v19, 0xffff0000, v49
	v_mul_f32_e32 v8, v8, v220
	v_mul_f32_e32 v9, v9, v221
	v_mul_f32_e32 v10, v10, v222
	v_mul_f32_e32 v11, v11, v223
	v_mul_f32_e32 v8, v8, v16
	v_mul_f32_e32 v9, v9, v17
	v_mul_f32_e32 v10, v10, v18
	v_mul_f32_e32 v11, v11, v19
	v_cvt_pk_bf16_f32 v8, v8, v9
	v_cvt_pk_bf16_f32 v9, v10, v11
	global_store_dwordx2 v[32:33], v[8:9], off offset:160
	v_lshlrev_b32_e32 v12, 16, v46
	v_and_b32_e32 v13, 0xffff0000, v46
	v_lshlrev_b32_e32 v14, 16, v47
	v_and_b32_e32 v15, 0xffff0000, v47
	v_mul_f32_e32 v0, v0, v224
	v_mul_f32_e32 v1, v1, v225
	v_mul_f32_e32 v2, v2, v226
	v_mul_f32_e32 v3, v3, v227
	v_mul_f32_e32 v0, v0, v12
	v_mul_f32_e32 v1, v1, v13
	v_mul_f32_e32 v2, v2, v14
	v_mul_f32_e32 v3, v3, v15
	v_cvt_pk_bf16_f32 v0, v0, v1
	v_cvt_pk_bf16_f32 v1, v2, v3
	global_store_dwordx2 v[32:33], v[0:1], off offset:192
	v_lshlrev_b32_e32 v8, 16, v44
	v_and_b32_e32 v9, 0xffff0000, v44
	v_lshlrev_b32_e32 v10, 16, v45
	v_and_b32_e32 v11, 0xffff0000, v45
	v_mul_f32_e32 v0, v4, v228
	v_mul_f32_e32 v1, v5, v229
	v_mul_f32_e32 v2, v6, v230
	v_mul_f32_e32 v3, v7, v231
	v_mul_f32_e32 v0, v0, v8
	v_mul_f32_e32 v1, v1, v9
	v_mul_f32_e32 v2, v2, v10
	v_mul_f32_e32 v3, v3, v11
	v_cvt_pk_bf16_f32 v0, v0, v1
	v_cvt_pk_bf16_f32 v1, v2, v3
	global_store_dwordx2 v[32:33], v[0:1], off offset:224
	s_barrier

.LBB0_845:
	s_or_b64 exec, exec, s[12:13]
	v_pk_mul_f32 v[80:81], v[28:29], v[28:29]
	v_pk_mul_f32 v[82:83], v[24:25], v[24:25]
	v_pk_mul_f32 v[76:77], v[30:31], v[30:31]
	v_pk_mul_f32 v[78:79], v[26:27], v[26:27]
	v_mov_b32_e32 v84, v80
	v_mov_b32_e32 v85, v82
	v_mov_b32_e32 v82, v81
	v_pk_add_f32 v[80:81], v[84:85], v[82:83]
	v_mov_b32_e32 v82, v76
	v_mov_b32_e32 v83, v78
	v_pk_mul_f32 v[72:73], v[16:17], v[16:17]
	v_pk_mul_f32 v[74:75], v[20:21], v[20:21]
	v_pk_add_f32 v[80:81], v[82:83], v[80:81]
	v_mov_b32_e32 v78, v77
	v_pk_mul_f32 v[68:69], v[18:19], v[18:19]
	v_pk_mul_f32 v[70:71], v[22:23], v[22:23]
	v_pk_add_f32 v[76:77], v[78:79], v[80:81]
	v_mov_b32_e32 v78, v72
	v_mov_b32_e32 v79, v74
	v_mov_b32_e32 v74, v73
	v_pk_add_f32 v[72:73], v[78:79], v[74:75]
	v_mov_b32_e32 v74, v68
	v_mov_b32_e32 v75, v70
	v_pk_mul_f32 v[62:63], v[8:9], v[8:9]
	v_pk_mul_f32 v[66:67], v[12:13], v[12:13]
	v_pk_add_f32 v[72:73], v[74:75], v[72:73]
	v_mov_b32_e32 v70, v69
	v_pk_mul_f32 v[40:41], v[10:11], v[10:11]
	v_pk_mul_f32 v[42:43], v[14:15], v[14:15]
	v_pk_add_f32 v[68:69], v[70:71], v[72:73]
	v_mov_b32_e32 v70, v62
	v_mov_b32_e32 v71, v66
	v_mov_b32_e32 v66, v63
	v_pk_add_f32 v[62:63], v[70:71], v[66:67]
	v_mov_b32_e32 v66, v40
	v_mov_b32_e32 v67, v42
	v_pk_mul_f32 v[36:37], v[0:1], v[0:1]
	v_pk_mul_f32 v[38:39], v[4:5], v[4:5]
	v_pk_add_f32 v[62:63], v[66:67], v[62:63]
	v_mov_b32_e32 v42, v41
	v_pk_mul_f32 v[32:33], v[2:3], v[2:3]
	v_pk_mul_f32 v[34:35], v[6:7], v[6:7]
	v_pk_add_f32 v[40:41], v[42:43], v[62:63]
	v_mov_b32_e32 v42, v36
	v_mov_b32_e32 v43, v38
	v_mov_b32_e32 v38, v37
	v_pk_add_f32 v[36:37], v[42:43], v[38:39]
	v_mov_b32_e32 v38, v32
	v_mov_b32_e32 v39, v34
	v_pk_add_f32 v[36:37], v[38:39], v[36:37]
	v_mov_b32_e32 v34, v33
	v_pk_add_f32 v[32:33], v[34:35], v[36:37]
	v_add_f32_e32 v34, v76, v77
	v_add_f32_e32 v34, v69, v34
	v_add_f32_e32 v34, v68, v34
	v_add_f32_e32 v34, v41, v34
	v_add_f32_e32 v34, v40, v34
	v_add_f32_e32 v33, v33, v34
	v_and_b32_e32 v34, 64, v183
	v_add_f32_e32 v32, v32, v33
	v_xor_b32_e32 v33, 16, v183
	v_add_u32_e32 v34, 64, v34
	v_cmp_lt_i32_e32 vcc, v33, v34
	s_lshl_b32 s0, s21, 2
	v_readlane_b32 s1, v249, 49
	v_cndmask_b32_e32 v33, v183, v33, vcc
	v_lshlrev_b32_e32 v33, 2, v33
	ds_bpermute_b32 v33, v33, v32
	v_ashrrev_i32_e32 v61, 31, v60
	s_add_u32 s12, s1, s0
	v_readlane_b32 s0, v249, 51
	s_addc_u32 s13, s0, 0
	v_lshlrev_b32_e32 v41, 2, v65
	global_load_dwordx4 v[200:203], v41, s[12:13]
	global_load_dwordx4 v[204:207], v41, s[12:13] offset:64
	global_load_dwordx4 v[208:211], v41, s[12:13] offset:128
	global_load_dwordx4 v[212:215], v41, s[12:13] offset:192
	global_load_dwordx4 v[216:219], v41, s[12:13] offset:256
	global_load_dwordx4 v[220:223], v41, s[12:13] offset:320
	global_load_dwordx4 v[224:227], v41, s[12:13] offset:384
	global_load_dwordx4 v[228:231], v41, s[12:13] offset:448
	s_waitcnt lgkmcnt(0)
	v_add_f32_e32 v32, v32, v33
	v_xor_b32_e32 v33, 32, v183
	v_cmp_lt_i32_e32 vcc, v33, v34
	v_mov_b64_e32 v[34:35], s[6:7]
	s_lshl_b32 s74, s21, 1
	v_cndmask_b32_e32 v33, v183, v33, vcc
	v_lshlrev_b32_e32 v33, 2, v33
	ds_bpermute_b32 v33, v33, v32
	v_lshlrev_b32_e32 v138, 1, v65
	v_lshlrev_b32_e32 v42, 16, v58
	v_and_b32_e32 v43, 0xffff0000, v58
	s_waitcnt lgkmcnt(0)
	v_add_f32_e32 v32, v32, v33
	v_fmamk_f32 v32, v32, 0x3c000000, v177
	v_cmp_gt_f32_e32 vcc, s28, v32
	v_mul_f32_e32 v33, 0x4b800000, v32
	v_lshlrev_b32_e32 v58, 16, v59
	v_cndmask_b32_e32 v32, v32, v33, vcc
	v_rsq_f32_e32 v32, v32
	v_and_b32_e32 v59, 0xffff0000, v59
	s_mov_b64 s[36:37], 0x1400
	s_add_i32 s20, s20, s96
	v_mul_f32_e32 v33, 0x45800000, v32
	v_cndmask_b32_e32 v40, v32, v33, vcc
	v_lshl_add_u64 v[32:33], s[38:39], 0, v[60:61]
	v_mad_u64_u32 v[34:35], s[0:1], v32, s22, v[34:35]
	v_mov_b32_e32 v32, v35
	v_mad_u64_u32 v[32:33], s[0:1], v33, s22, v[32:33]
	v_mov_b32_e32 v35, v32
	v_lshl_add_u64 v[32:33], v[34:35], 0, s[74:75]
	v_lshl_add_u64 v[38:39], v[32:33], 0, v[138:139]
	v_mul_f32_e32 v28, v28, v40
	v_mul_f32_e32 v29, v29, v40
	v_mul_f32_e32 v24, v24, v40
	v_mul_f32_e32 v25, v25, v40
	v_lshl_add_u64 v[36:37], v[38:39], 0, s[36:37]
	v_mul_f32_e32 v20, v20, v40
	v_mul_f32_e32 v21, v21, v40
	v_mul_f32_e32 v16, v16, v40
	v_mul_f32_e32 v17, v17, v40
	v_mul_f32_e32 v12, v12, v40
	v_mul_f32_e32 v13, v13, v40
	v_mul_f32_e32 v8, v8, v40
	v_mul_f32_e32 v9, v9, v40
	v_mul_f32_e32 v4, v4, v40
	v_mul_f32_e32 v5, v5, v40
	v_mul_f32_e32 v0, v0, v40
	v_mul_f32_e32 v1, v1, v40
	s_cmpk_gt_i32 s20, 0x1ff
	s_waitcnt vmcnt(0)
	v_mul_f32_e32 v28, v200, v28
	v_mul_f32_e32 v29, v201, v29
	v_mul_f32_e32 v28, v28, v42
	v_mul_f32_e32 v29, v29, v43
	v_cvt_pk_bf16_f32 v28, v28, v29
	v_mul_f32_e32 v29, v30, v40
	v_mul_f32_e32 v30, v31, v40
	v_mul_f32_e32 v29, v202, v29
	v_mul_f32_e32 v30, v203, v30
	v_mul_f32_e32 v29, v29, v58
	v_mul_f32_e32 v30, v30, v59
	v_cvt_pk_bf16_f32 v29, v29, v30
	v_add_co_u32_e32 v30, vcc, s97, v38
	v_lshlrev_b32_e32 v32, 16, v56
	s_nop 0
	v_addc_co_u32_e32 v31, vcc, 0, v39, vcc
	global_store_dwordx2 v[30:31], v[28:29], off offset:1024
	v_and_b32_e32 v33, 0xffff0000, v56
	v_lshlrev_b32_e32 v34, 16, v57
	v_and_b32_e32 v35, 0xffff0000, v57
	v_mul_f32_e32 v24, v204, v24
	v_mul_f32_e32 v25, v205, v25
	v_mul_f32_e32 v24, v24, v32
	v_mul_f32_e32 v25, v25, v33
	v_cvt_pk_bf16_f32 v24, v24, v25
	v_mul_f32_e32 v25, v26, v40
	v_mul_f32_e32 v25, v206, v25
	v_mul_f32_e32 v26, v27, v40
	v_mul_f32_e32 v25, v25, v34
	v_mul_f32_e32 v26, v207, v26
	v_mul_f32_e32 v26, v26, v35
	v_cvt_pk_bf16_f32 v25, v25, v26
	global_store_dwordx2 v[36:37], v[24:25], off offset:32
	v_lshlrev_b32_e32 v28, 16, v54
	v_and_b32_e32 v29, 0xffff0000, v54
	v_lshlrev_b32_e32 v30, 16, v55
	v_and_b32_e32 v31, 0xffff0000, v55
	v_mul_f32_e32 v20, v208, v20
	v_mul_f32_e32 v21, v209, v21
	v_mul_f32_e32 v20, v20, v28
	v_mul_f32_e32 v21, v21, v29
	v_cvt_pk_bf16_f32 v20, v20, v21
	v_mul_f32_e32 v21, v22, v40
	v_mul_f32_e32 v21, v210, v21
	v_mul_f32_e32 v22, v23, v40
	v_mul_f32_e32 v21, v21, v30
	v_mul_f32_e32 v22, v211, v22
	v_mul_f32_e32 v22, v22, v31
	v_cvt_pk_bf16_f32 v21, v21, v22
	global_store_dwordx2 v[36:37], v[20:21], off offset:64
	v_lshlrev_b32_e32 v24, 16, v52
	v_and_b32_e32 v25, 0xffff0000, v52
	v_lshlrev_b32_e32 v26, 16, v53
	v_and_b32_e32 v27, 0xffff0000, v53
	v_mul_f32_e32 v16, v212, v16
	v_mul_f32_e32 v17, v213, v17
	v_mul_f32_e32 v16, v16, v24
	v_mul_f32_e32 v17, v17, v25
	v_cvt_pk_bf16_f32 v16, v16, v17
	v_mul_f32_e32 v17, v18, v40
	v_mul_f32_e32 v17, v214, v17
	v_mul_f32_e32 v18, v19, v40
	v_mul_f32_e32 v17, v17, v26
	v_mul_f32_e32 v18, v215, v18
	v_mul_f32_e32 v18, v18, v27
	v_cvt_pk_bf16_f32 v17, v17, v18
	global_store_dwordx2 v[36:37], v[16:17], off offset:96
	v_lshlrev_b32_e32 v20, 16, v50
	v_and_b32_e32 v21, 0xffff0000, v50
	v_lshlrev_b32_e32 v22, 16, v51
	v_and_b32_e32 v23, 0xffff0000, v51
	v_mul_f32_e32 v12, v216, v12
	v_mul_f32_e32 v13, v217, v13
	v_mul_f32_e32 v12, v12, v20
	v_mul_f32_e32 v13, v13, v21
	v_cvt_pk_bf16_f32 v12, v12, v13
	v_mul_f32_e32 v13, v14, v40
	v_mul_f32_e32 v13, v218, v13
	v_mul_f32_e32 v14, v15, v40
	v_mul_f32_e32 v13, v13, v22
	v_mul_f32_e32 v14, v219, v14
	v_mul_f32_e32 v14, v14, v23
	v_cvt_pk_bf16_f32 v13, v13, v14
	global_store_dwordx2 v[36:37], v[12:13], off offset:128
	v_lshlrev_b32_e32 v16, 16, v48
	v_and_b32_e32 v17, 0xffff0000, v48
	v_lshlrev_b32_e32 v18, 16, v49
	v_and_b32_e32 v19, 0xffff0000, v49
	v_mul_f32_e32 v8, v8, v220
	v_mul_f32_e32 v9, v9, v221
	v_mul_f32_e32 v8, v8, v16
	v_mul_f32_e32 v9, v9, v17
	v_cvt_pk_bf16_f32 v8, v8, v9
	v_mul_f32_e32 v9, v10, v40
	v_mul_f32_e32 v9, v9, v222
	v_mul_f32_e32 v10, v11, v40
	v_mul_f32_e32 v9, v9, v18
	v_mul_f32_e32 v10, v10, v223
	v_mul_f32_e32 v10, v10, v19
	v_cvt_pk_bf16_f32 v9, v9, v10
	global_store_dwordx2 v[36:37], v[8:9], off offset:160
	v_lshlrev_b32_e32 v12, 16, v46
	v_and_b32_e32 v13, 0xffff0000, v46
	v_lshlrev_b32_e32 v14, 16, v47
	v_and_b32_e32 v15, 0xffff0000, v47
	v_mul_f32_e32 v4, v4, v224
	v_mul_f32_e32 v5, v5, v225
	v_mul_f32_e32 v4, v4, v12
	v_mul_f32_e32 v5, v5, v13
	v_cvt_pk_bf16_f32 v4, v4, v5
	v_mul_f32_e32 v5, v6, v40
	v_mul_f32_e32 v5, v5, v226
	v_mul_f32_e32 v6, v7, v40
	v_mul_f32_e32 v5, v5, v14
	v_mul_f32_e32 v6, v6, v227
	v_mul_f32_e32 v6, v6, v15
	v_cvt_pk_bf16_f32 v5, v5, v6
	global_store_dwordx2 v[36:37], v[4:5], off offset:192
	v_lshlrev_b32_e32 v8, 16, v44
	v_and_b32_e32 v9, 0xffff0000, v44
	v_lshlrev_b32_e32 v10, 16, v45
	v_and_b32_e32 v11, 0xffff0000, v45
	v_mul_f32_e32 v0, v0, v228
	v_mul_f32_e32 v1, v1, v229
	v_mul_f32_e32 v0, v0, v8
	v_mul_f32_e32 v1, v1, v9
	v_cvt_pk_bf16_f32 v0, v0, v1
	v_mul_f32_e32 v1, v2, v40
	v_mul_f32_e32 v1, v1, v230
	v_mul_f32_e32 v2, v3, v40
	v_mul_f32_e32 v1, v1, v10
	v_mul_f32_e32 v2, v2, v231
	v_mul_f32_e32 v2, v2, v11
	v_cvt_pk_bf16_f32 v1, v1, v2
	global_store_dwordx2 v[36:37], v[0:1], off offset:224
	s_barrier
	s_cbranch_scc1 .LBB0_841
